# P8 row pass: all twelve loop rows of a wave loaded up front, groups of four, packed f32 + DPP
# speedup vs baseline: 1.0007x; 1.0007x over previous
; __device__ __forceinline__ float bf_lo(unsigned w) { return __uint_as_float(w << 16); }
; __device__ __forceinline__ float bf_hi(unsigned w) { return __uint_as_float(w & 0xffff0000u); }
;     __device__ __forceinline__ const float* in(int i) const { return karg_in(i); }
; #define FTID const int ftid_ = fresh_tid()
; template <int R>
; __device__ __forceinline__ void rows_norm512(bf16* base, int m0, int stride, int mx, const float* g, int lane) {
;     v4u w[R]; float ss[R]; int mr[R]; bool ok[R];
; #pragma unroll
;     for (int r = 0; r < R; ++r) { mr[r] = (r == 4) ? mx : m0 + r * stride; ok[r] = (r == 4) ? (mx < M) : (mr[r] < MPROMPT);
;         w[r] = *(const v4u*)(base + (size_t)(ok[r] ? mr[r] : 0) * DM + 8 * lane); }
;     const v4f g0 = *(const v4f*)(g + 8 * lane), g1 = *(const v4f*)(g + 8 * lane + 4);
; #pragma unroll
;     for (int r = 0; r < R; ++r) { const v4u x = w[r];
;         ss[r] = (bf_lo(x.x) * bf_lo(x.x) + bf_hi(x.x) * bf_hi(x.x)) + (bf_lo(x.y) * bf_lo(x.y) + bf_hi(x.y) * bf_hi(x.y)) + (bf_lo(x.z) * bf_lo(x.z) + bf_hi(x.z) * bf_hi(x.z)) + (bf_lo(x.w) * bf_lo(x.w) + bf_hi(x.w) * bf_hi(x.w)); }
; #pragma unroll
;     for (int r = 0; r < R; ++r) ss[r] = rsqrtf(wave_sum(ss[r]) * (1.f / 512.f) + EPS);
; __global__ void __launch_bounds__(NTHREADS, 2) fwd_kernel(Args args) {
;     ...
;     { FTID; const float* gb = C.in(25); bf16* bb_ = C.MIX() + AW; const int gw_ = GWV, ngw_ = NGWV, nit = (MPROMPT + 4 * ngw_ - 1) / (4 * ngw_);
;       for (int it = 0; it < nit - 1; ++it) rows_norm512<4>(bb_, gw_ + 4 * it * ngw_, ngw_, M, gb, LANE);
.LBB0_823:
	s_or_b64 exec, exec, s[8:9]
	v_mov_b32_e32 v58, v182
	s_mov_b64 s[0:1], s[80:81]
	s_waitcnt lgkmcnt(0)
	s_barrier
	s_load_dwordx2 s[12:13], s[0:1], 0xc8
	s_mov_b64 s[0:1], s[80:81]
	s_load_dwordx2 s[10:11], s[0:1], 0x110
	v_readfirstlane_b32 s0, v58
	v_lshlrev_b32_e32 v0, 3, v58
	v_and_b32_e32 v0, 0x1f8, v0
	v_mov_b32_e32 v13, 0
	s_waitcnt lgkmcnt(0)
	s_add_u32 s16, s10, 0x16400400
	s_addc_u32 s17, s11, 0
	s_ashr_i32 s34, s0, 6
	v_readlane_b32 s0, v232, 0
	s_add_i32 s35, s34, s0
	s_and_b64 vcc, exec, s[6:7]
	v_lshlrev_b32_e32 v12, 1, v0
	v_lshlrev_b32_e32 v14, 2, v0
	v_and_b32_e32 v163, 63, v182
	v_lshlrev_b32_e32 v161, 4, v163
	s_lshl_b32 vcc_lo, s35, 11
	v_lshlrev_b32_e32 v163, 5, v163
	v_add_u32_e32 v161, vcc_lo, v161
	v_add_u32_e32 v161, 0x16400400, v161
	v_mov_b32_e32 v162, v161
	v_mov_b32_e32 v160, 0x358637bd
	global_load_dwordx4 v[108:111], v163, s[12:13]
	global_load_dwordx4 v[112:115], v163, s[12:13] offset:16
	global_load_dwordx4 v[60:63], v161, s[10:11]
	v_add_u32_e32 v161, 0x400000, v161
	global_load_dwordx4 v[64:67], v161, s[10:11]
	v_add_u32_e32 v161, 0x400000, v161
	global_load_dwordx4 v[68:71], v161, s[10:11]
	v_add_u32_e32 v161, 0x400000, v161
	global_load_dwordx4 v[72:75], v161, s[10:11]
	v_add_u32_e32 v161, 0x400000, v161
	global_load_dwordx4 v[76:79], v161, s[10:11]
	v_add_u32_e32 v161, 0x400000, v161
	global_load_dwordx4 v[80:83], v161, s[10:11]
	v_add_u32_e32 v161, 0x400000, v161
	global_load_dwordx4 v[84:87], v161, s[10:11]
	v_add_u32_e32 v161, 0x400000, v161
	global_load_dwordx4 v[88:91], v161, s[10:11]
	v_add_u32_e32 v161, 0x400000, v161
	global_load_dwordx4 v[92:95], v161, s[10:11]
	v_add_u32_e32 v161, 0x400000, v161
	global_load_dwordx4 v[96:99], v161, s[10:11]
	v_add_u32_e32 v161, 0x400000, v161
	global_load_dwordx4 v[100:103], v161, s[10:11]
	v_add_u32_e32 v161, 0x400000, v161
	global_load_dwordx4 v[104:107], v161, s[10:11]
	v_add_u32_e32 v161, 0x400000, v161
	s_waitcnt vmcnt(8)
	v_lshlrev_b32_e32 v116, 16, v60
	v_and_b32_e32 v117, 0xffff0000, v60
	v_lshlrev_b32_e32 v118, 16, v61
	v_and_b32_e32 v119, 0xffff0000, v61
	v_lshlrev_b32_e32 v120, 16, v62
	v_and_b32_e32 v121, 0xffff0000, v62
	v_lshlrev_b32_e32 v122, 16, v63
	v_and_b32_e32 v123, 0xffff0000, v63
	v_pk_mul_f32 v[148:149], v[116:117], v[116:117]
	v_pk_fma_f32 v[148:149], v[118:119], v[118:119], v[148:149]
	v_pk_fma_f32 v[148:149], v[120:121], v[120:121], v[148:149]
	v_pk_fma_f32 v[148:149], v[122:123], v[122:123], v[148:149]
	s_nop 0
	v_add_f32_e32 v148, v148, v149
	v_lshlrev_b32_e32 v124, 16, v64
	v_and_b32_e32 v125, 0xffff0000, v64
	v_lshlrev_b32_e32 v126, 16, v65
	v_and_b32_e32 v127, 0xffff0000, v65
	v_lshlrev_b32_e32 v128, 16, v66
	v_and_b32_e32 v129, 0xffff0000, v66
	v_lshlrev_b32_e32 v130, 16, v67
	v_and_b32_e32 v131, 0xffff0000, v67
	v_pk_mul_f32 v[150:151], v[124:125], v[124:125]
	v_pk_fma_f32 v[150:151], v[126:127], v[126:127], v[150:151]
	v_pk_fma_f32 v[150:151], v[128:129], v[128:129], v[150:151]
	v_pk_fma_f32 v[150:151], v[130:131], v[130:131], v[150:151]
	s_nop 0
	v_add_f32_e32 v150, v150, v151
	v_lshlrev_b32_e32 v132, 16, v68
	v_and_b32_e32 v133, 0xffff0000, v68
	v_lshlrev_b32_e32 v134, 16, v69
	v_and_b32_e32 v135, 0xffff0000, v69
	v_lshlrev_b32_e32 v136, 16, v70
	v_and_b32_e32 v137, 0xffff0000, v70
	v_lshlrev_b32_e32 v138, 16, v71
	v_and_b32_e32 v139, 0xffff0000, v71
	v_pk_mul_f32 v[152:153], v[132:133], v[132:133]
	v_pk_fma_f32 v[152:153], v[134:135], v[134:135], v[152:153]
	v_pk_fma_f32 v[152:153], v[136:137], v[136:137], v[152:153]
	v_pk_fma_f32 v[152:153], v[138:139], v[138:139], v[152:153]
	s_nop 0
	v_add_f32_e32 v152, v152, v153
	v_lshlrev_b32_e32 v140, 16, v72
	v_and_b32_e32 v141, 0xffff0000, v72
	v_lshlrev_b32_e32 v142, 16, v73
	v_and_b32_e32 v143, 0xffff0000, v73
	v_lshlrev_b32_e32 v144, 16, v74
	v_and_b32_e32 v145, 0xffff0000, v74
	v_lshlrev_b32_e32 v146, 16, v75
	v_and_b32_e32 v147, 0xffff0000, v75
	v_pk_mul_f32 v[154:155], v[140:141], v[140:141]
	v_pk_fma_f32 v[154:155], v[142:143], v[142:143], v[154:155]
	v_pk_fma_f32 v[154:155], v[144:145], v[144:145], v[154:155]
	v_pk_fma_f32 v[154:155], v[146:147], v[146:147], v[154:155]
	s_nop 0
	v_add_f32_e32 v154, v154, v155
	s_nop 1
	v_add_f32_dpp v148, v148, v148 quad_perm:[1,0,3,2] row_mask:0xf bank_mask:0xf
	v_add_f32_dpp v150, v150, v150 quad_perm:[1,0,3,2] row_mask:0xf bank_mask:0xf
	v_add_f32_dpp v152, v152, v152 quad_perm:[1,0,3,2] row_mask:0xf bank_mask:0xf
	v_add_f32_dpp v154, v154, v154 quad_perm:[1,0,3,2] row_mask:0xf bank_mask:0xf
	v_add_f32_dpp v148, v148, v148 quad_perm:[2,3,0,1] row_mask:0xf bank_mask:0xf
	v_add_f32_dpp v150, v150, v150 quad_perm:[2,3,0,1] row_mask:0xf bank_mask:0xf
	v_add_f32_dpp v152, v152, v152 quad_perm:[2,3,0,1] row_mask:0xf bank_mask:0xf
	v_add_f32_dpp v154, v154, v154 quad_perm:[2,3,0,1] row_mask:0xf bank_mask:0xf
	v_add_f32_dpp v148, v148, v148 row_half_mirror row_mask:0xf bank_mask:0xf
	v_add_f32_dpp v150, v150, v150 row_half_mirror row_mask:0xf bank_mask:0xf
	v_add_f32_dpp v152, v152, v152 row_half_mirror row_mask:0xf bank_mask:0xf
	v_add_f32_dpp v154, v154, v154 row_half_mirror row_mask:0xf bank_mask:0xf
	v_add_f32_dpp v148, v148, v148 row_mirror row_mask:0xf bank_mask:0xf
	v_add_f32_dpp v150, v150, v150 row_mirror row_mask:0xf bank_mask:0xf
	v_add_f32_dpp v152, v152, v152 row_mirror row_mask:0xf bank_mask:0xf
	v_add_f32_dpp v154, v154, v154 row_mirror row_mask:0xf bank_mask:0xf
	ds_bpermute_b32 v156, v187, v148
	ds_bpermute_b32 v157, v187, v150
	ds_bpermute_b32 v158, v187, v152
	ds_bpermute_b32 v159, v187, v154
	s_waitcnt lgkmcnt(0)
; __device__ __forceinline__ float bf_lo(unsigned w) { return __uint_as_float(w << 16); }
; __device__ __forceinline__ float bf_hi(unsigned w) { return __uint_as_float(w & 0xffff0000u); }
; __device__ __forceinline__ unsigned cvt_pk_nv(float lo, float hi) { unsigned r; asm("v_cvt_pk_bf16_f32 %0, %1, %2" : "=v"(r) : "v"(lo), "v"(hi)); return r; }
; template <int R>
; __device__ __forceinline__ void rows_norm512(bf16* base, int m0, int stride, int mx, const float* g, int lane) {
;     ...
;     const v4f g0 = *(const v4f*)(g + 8 * lane), g1 = *(const v4f*)(g + 8 * lane + 4);
; #pragma unroll
;     for (int r = 0; r < R; ++r) { const v4u x = w[r];
;         ss[r] = (bf_lo(x.x) * bf_lo(x.x) + bf_hi(x.x) * bf_hi(x.x)) + (bf_lo(x.y) * bf_lo(x.y) + bf_hi(x.y) * bf_hi(x.y)) + (bf_lo(x.z) * bf_lo(x.z) + bf_hi(x.z) * bf_hi(x.z)) + (bf_lo(x.w) * bf_lo(x.w) + bf_hi(x.w) * bf_hi(x.w)); }
; #pragma unroll
;     for (int r = 0; r < R; ++r) ss[r] = rsqrtf(wave_sum(ss[r]) * (1.f / 512.f) + EPS);
; #pragma unroll
;     for (int r = 0; r < R; ++r) { const v4u x = w[r]; const float q = ss[r];
;         v4u o; o.x = cvt_pk_nv(bf_lo(x.x) * q * g0.x, bf_hi(x.x) * q * g0.y); o.y = cvt_pk_nv(bf_lo(x.y) * q * g0.z, bf_hi(x.y) * q * g0.w);
;         o.z = cvt_pk_nv(bf_lo(x.z) * q * g1.x, bf_hi(x.z) * q * g1.y); o.w = cvt_pk_nv(bf_lo(x.w) * q * g1.z, bf_hi(x.w) * q * g1.w);
;         if (ok[r]) *(v4u*)(base + (size_t)mr[r] * DM + 8 * lane) = o; }
	v_add_f32_e32 v148, v148, v156
	v_add_f32_e32 v150, v150, v157
	v_add_f32_e32 v152, v152, v158
	v_add_f32_e32 v154, v154, v159
	ds_bpermute_b32 v156, v188, v148
	ds_bpermute_b32 v157, v188, v150
	ds_bpermute_b32 v158, v188, v152
	ds_bpermute_b32 v159, v188, v154
	s_waitcnt lgkmcnt(0)
	v_add_f32_e32 v148, v148, v156
	v_add_f32_e32 v150, v150, v157
	v_add_f32_e32 v152, v152, v158
	v_add_f32_e32 v154, v154, v159
	v_fmamk_f32 v148, v148, 0x3b000000, v160
	v_fmamk_f32 v150, v150, 0x3b000000, v160
	v_fmamk_f32 v152, v152, 0x3b000000, v160
	v_fmamk_f32 v154, v154, 0x3b000000, v160
	v_rsq_f32_e32 v148, v148
	v_rsq_f32_e32 v150, v150
	v_rsq_f32_e32 v152, v152
	v_rsq_f32_e32 v154, v154
	s_nop 1
	v_pk_mul_f32 v[164:165], v[116:117], v[148:149] op_sel_hi:[1,0]
	v_pk_mul_f32 v[166:167], v[118:119], v[148:149] op_sel_hi:[1,0]
	v_pk_mul_f32 v[168:169], v[120:121], v[148:149] op_sel_hi:[1,0]
	v_pk_mul_f32 v[170:171], v[122:123], v[148:149] op_sel_hi:[1,0]
	v_pk_mul_f32 v[164:165], v[164:165], v[108:109]
	v_pk_mul_f32 v[166:167], v[166:167], v[110:111]
	v_pk_mul_f32 v[168:169], v[168:169], v[112:113]
	v_pk_mul_f32 v[170:171], v[170:171], v[114:115]
	v_cvt_pk_bf16_f32 v20, v164, v165
	v_cvt_pk_bf16_f32 v21, v166, v167
	v_cvt_pk_bf16_f32 v22, v168, v169
	v_cvt_pk_bf16_f32 v23, v170, v171
	global_store_dwordx4 v162, v[20:23], s[10:11]
	v_add_u32_e32 v162, 0x400000, v162
	v_pk_mul_f32 v[164:165], v[124:125], v[150:151] op_sel_hi:[1,0]
	v_pk_mul_f32 v[166:167], v[126:127], v[150:151] op_sel_hi:[1,0]
	v_pk_mul_f32 v[168:169], v[128:129], v[150:151] op_sel_hi:[1,0]
	v_pk_mul_f32 v[170:171], v[130:131], v[150:151] op_sel_hi:[1,0]
	v_pk_mul_f32 v[164:165], v[164:165], v[108:109]
	v_pk_mul_f32 v[166:167], v[166:167], v[110:111]
	v_pk_mul_f32 v[168:169], v[168:169], v[112:113]
	v_pk_mul_f32 v[170:171], v[170:171], v[114:115]
	v_cvt_pk_bf16_f32 v24, v164, v165
	v_cvt_pk_bf16_f32 v25, v166, v167
	v_cvt_pk_bf16_f32 v26, v168, v169
	v_cvt_pk_bf16_f32 v27, v170, v171
	global_store_dwordx4 v162, v[24:27], s[10:11]
	v_add_u32_e32 v162, 0x400000, v162
	v_pk_mul_f32 v[164:165], v[132:133], v[152:153] op_sel_hi:[1,0]
	v_pk_mul_f32 v[166:167], v[134:135], v[152:153] op_sel_hi:[1,0]
	v_pk_mul_f32 v[168:169], v[136:137], v[152:153] op_sel_hi:[1,0]
	v_pk_mul_f32 v[170:171], v[138:139], v[152:153] op_sel_hi:[1,0]
	v_pk_mul_f32 v[164:165], v[164:165], v[108:109]
	v_pk_mul_f32 v[166:167], v[166:167], v[110:111]
	v_pk_mul_f32 v[168:169], v[168:169], v[112:113]
	v_pk_mul_f32 v[170:171], v[170:171], v[114:115]
	v_cvt_pk_bf16_f32 v28, v164, v165
	v_cvt_pk_bf16_f32 v29, v166, v167
	v_cvt_pk_bf16_f32 v30, v168, v169
	v_cvt_pk_bf16_f32 v31, v170, v171
	global_store_dwordx4 v162, v[28:31], s[10:11]
	v_add_u32_e32 v162, 0x400000, v162
	v_pk_mul_f32 v[164:165], v[140:141], v[154:155] op_sel_hi:[1,0]
	v_pk_mul_f32 v[166:167], v[142:143], v[154:155] op_sel_hi:[1,0]
	v_pk_mul_f32 v[168:169], v[144:145], v[154:155] op_sel_hi:[1,0]
	v_pk_mul_f32 v[170:171], v[146:147], v[154:155] op_sel_hi:[1,0]
	v_pk_mul_f32 v[164:165], v[164:165], v[108:109]
	v_pk_mul_f32 v[166:167], v[166:167], v[110:111]
	v_pk_mul_f32 v[168:169], v[168:169], v[112:113]
	v_pk_mul_f32 v[170:171], v[170:171], v[114:115]
	v_cvt_pk_bf16_f32 v32, v164, v165
	v_cvt_pk_bf16_f32 v33, v166, v167
	v_cvt_pk_bf16_f32 v34, v168, v169
	v_cvt_pk_bf16_f32 v35, v170, v171
	global_store_dwordx4 v162, v[32:35], s[10:11]
	v_add_u32_e32 v162, 0x400000, v162
	s_waitcnt vmcnt(8)
	v_lshlrev_b32_e32 v116, 16, v76
	v_and_b32_e32 v117, 0xffff0000, v76
	v_lshlrev_b32_e32 v118, 16, v77
	v_and_b32_e32 v119, 0xffff0000, v77
	v_lshlrev_b32_e32 v120, 16, v78
	v_and_b32_e32 v121, 0xffff0000, v78
	v_lshlrev_b32_e32 v122, 16, v79
	v_and_b32_e32 v123, 0xffff0000, v79
	v_pk_mul_f32 v[148:149], v[116:117], v[116:117]
	v_pk_fma_f32 v[148:149], v[118:119], v[118:119], v[148:149]
	v_pk_fma_f32 v[148:149], v[120:121], v[120:121], v[148:149]
	v_pk_fma_f32 v[148:149], v[122:123], v[122:123], v[148:149]
	s_nop 0
	v_add_f32_e32 v148, v148, v149
	v_lshlrev_b32_e32 v124, 16, v80
	v_and_b32_e32 v125, 0xffff0000, v80
	v_lshlrev_b32_e32 v126, 16, v81
	v_and_b32_e32 v127, 0xffff0000, v81
	v_lshlrev_b32_e32 v128, 16, v82
	v_and_b32_e32 v129, 0xffff0000, v82
	v_lshlrev_b32_e32 v130, 16, v83
	v_and_b32_e32 v131, 0xffff0000, v83
	v_pk_mul_f32 v[150:151], v[124:125], v[124:125]
	v_pk_fma_f32 v[150:151], v[126:127], v[126:127], v[150:151]
	v_pk_fma_f32 v[150:151], v[128:129], v[128:129], v[150:151]
	v_pk_fma_f32 v[150:151], v[130:131], v[130:131], v[150:151]
	s_nop 0
	v_add_f32_e32 v150, v150, v151
	v_lshlrev_b32_e32 v132, 16, v84
	v_and_b32_e32 v133, 0xffff0000, v84
	v_lshlrev_b32_e32 v134, 16, v85
	v_and_b32_e32 v135, 0xffff0000, v85
	v_lshlrev_b32_e32 v136, 16, v86
	v_and_b32_e32 v137, 0xffff0000, v86
	v_lshlrev_b32_e32 v138, 16, v87
	v_and_b32_e32 v139, 0xffff0000, v87
	v_pk_mul_f32 v[152:153], v[132:133], v[132:133]
	v_pk_fma_f32 v[152:153], v[134:135], v[134:135], v[152:153]
	v_pk_fma_f32 v[152:153], v[136:137], v[136:137], v[152:153]
	v_pk_fma_f32 v[152:153], v[138:139], v[138:139], v[152:153]
	s_nop 0
	v_add_f32_e32 v152, v152, v153
	v_lshlrev_b32_e32 v140, 16, v88
	v_and_b32_e32 v141, 0xffff0000, v88
	v_lshlrev_b32_e32 v142, 16, v89
	v_and_b32_e32 v143, 0xffff0000, v89
	v_lshlrev_b32_e32 v144, 16, v90
	v_and_b32_e32 v145, 0xffff0000, v90
	v_lshlrev_b32_e32 v146, 16, v91
	v_and_b32_e32 v147, 0xffff0000, v91
	v_pk_mul_f32 v[154:155], v[140:141], v[140:141]
	v_pk_fma_f32 v[154:155], v[142:143], v[142:143], v[154:155]
	v_pk_fma_f32 v[154:155], v[144:145], v[144:145], v[154:155]
	v_pk_fma_f32 v[154:155], v[146:147], v[146:147], v[154:155]
	s_nop 0
	v_add_f32_e32 v154, v154, v155
	s_nop 1
	v_add_f32_dpp v148, v148, v148 quad_perm:[1,0,3,2] row_mask:0xf bank_mask:0xf
	v_add_f32_dpp v150, v150, v150 quad_perm:[1,0,3,2] row_mask:0xf bank_mask:0xf
	v_add_f32_dpp v152, v152, v152 quad_perm:[1,0,3,2] row_mask:0xf bank_mask:0xf
	v_add_f32_dpp v154, v154, v154 quad_perm:[1,0,3,2] row_mask:0xf bank_mask:0xf
	v_add_f32_dpp v148, v148, v148 quad_perm:[2,3,0,1] row_mask:0xf bank_mask:0xf
	v_add_f32_dpp v150, v150, v150 quad_perm:[2,3,0,1] row_mask:0xf bank_mask:0xf
	v_add_f32_dpp v152, v152, v152 quad_perm:[2,3,0,1] row_mask:0xf bank_mask:0xf
	v_add_f32_dpp v154, v154, v154 quad_perm:[2,3,0,1] row_mask:0xf bank_mask:0xf
	v_add_f32_dpp v148, v148, v148 row_half_mirror row_mask:0xf bank_mask:0xf
	v_add_f32_dpp v150, v150, v150 row_half_mirror row_mask:0xf bank_mask:0xf
	v_add_f32_dpp v152, v152, v152 row_half_mirror row_mask:0xf bank_mask:0xf
	v_add_f32_dpp v154, v154, v154 row_half_mirror row_mask:0xf bank_mask:0xf
	v_add_f32_dpp v148, v148, v148 row_mirror row_mask:0xf bank_mask:0xf
	v_add_f32_dpp v150, v150, v150 row_mirror row_mask:0xf bank_mask:0xf
	v_add_f32_dpp v152, v152, v152 row_mirror row_mask:0xf bank_mask:0xf
	v_add_f32_dpp v154, v154, v154 row_mirror row_mask:0xf bank_mask:0xf
	ds_bpermute_b32 v156, v187, v148
	ds_bpermute_b32 v157, v187, v150
	ds_bpermute_b32 v158, v187, v152
	ds_bpermute_b32 v159, v187, v154
	s_waitcnt lgkmcnt(0)
; __device__ __forceinline__ float bf_lo(unsigned w) { return __uint_as_float(w << 16); }
; __device__ __forceinline__ float bf_hi(unsigned w) { return __uint_as_float(w & 0xffff0000u); }
; __device__ __forceinline__ unsigned cvt_pk_nv(float lo, float hi) { unsigned r; asm("v_cvt_pk_bf16_f32 %0, %1, %2" : "=v"(r) : "v"(lo), "v"(hi)); return r; }
; template <int R>
; __device__ __forceinline__ void rows_norm512(bf16* base, int m0, int stride, int mx, const float* g, int lane) {
;     ...
;     const v4f g0 = *(const v4f*)(g + 8 * lane), g1 = *(const v4f*)(g + 8 * lane + 4);
; #pragma unroll
;     for (int r = 0; r < R; ++r) { const v4u x = w[r];
;         ss[r] = (bf_lo(x.x) * bf_lo(x.x) + bf_hi(x.x) * bf_hi(x.x)) + (bf_lo(x.y) * bf_lo(x.y) + bf_hi(x.y) * bf_hi(x.y)) + (bf_lo(x.z) * bf_lo(x.z) + bf_hi(x.z) * bf_hi(x.z)) + (bf_lo(x.w) * bf_lo(x.w) + bf_hi(x.w) * bf_hi(x.w)); }
; #pragma unroll
;     for (int r = 0; r < R; ++r) ss[r] = rsqrtf(wave_sum(ss[r]) * (1.f / 512.f) + EPS);
; #pragma unroll
;     for (int r = 0; r < R; ++r) { const v4u x = w[r]; const float q = ss[r];
;         v4u o; o.x = cvt_pk_nv(bf_lo(x.x) * q * g0.x, bf_hi(x.x) * q * g0.y); o.y = cvt_pk_nv(bf_lo(x.y) * q * g0.z, bf_hi(x.y) * q * g0.w);
;         o.z = cvt_pk_nv(bf_lo(x.z) * q * g1.x, bf_hi(x.z) * q * g1.y); o.w = cvt_pk_nv(bf_lo(x.w) * q * g1.z, bf_hi(x.w) * q * g1.w);
;         if (ok[r]) *(v4u*)(base + (size_t)mr[r] * DM + 8 * lane) = o; }
	v_add_f32_e32 v148, v148, v156
	v_add_f32_e32 v150, v150, v157
	v_add_f32_e32 v152, v152, v158
	v_add_f32_e32 v154, v154, v159
	ds_bpermute_b32 v156, v188, v148
	ds_bpermute_b32 v157, v188, v150
	ds_bpermute_b32 v158, v188, v152
	ds_bpermute_b32 v159, v188, v154
	s_waitcnt lgkmcnt(0)
	v_add_f32_e32 v148, v148, v156
	v_add_f32_e32 v150, v150, v157
	v_add_f32_e32 v152, v152, v158
	v_add_f32_e32 v154, v154, v159
	v_fmamk_f32 v148, v148, 0x3b000000, v160
	v_fmamk_f32 v150, v150, 0x3b000000, v160
	v_fmamk_f32 v152, v152, 0x3b000000, v160
	v_fmamk_f32 v154, v154, 0x3b000000, v160
	v_rsq_f32_e32 v148, v148
	v_rsq_f32_e32 v150, v150
	v_rsq_f32_e32 v152, v152
	v_rsq_f32_e32 v154, v154
	s_nop 1
	v_pk_mul_f32 v[164:165], v[116:117], v[148:149] op_sel_hi:[1,0]
	v_pk_mul_f32 v[166:167], v[118:119], v[148:149] op_sel_hi:[1,0]
	v_pk_mul_f32 v[168:169], v[120:121], v[148:149] op_sel_hi:[1,0]
	v_pk_mul_f32 v[170:171], v[122:123], v[148:149] op_sel_hi:[1,0]
	v_pk_mul_f32 v[164:165], v[164:165], v[108:109]
	v_pk_mul_f32 v[166:167], v[166:167], v[110:111]
	v_pk_mul_f32 v[168:169], v[168:169], v[112:113]
	v_pk_mul_f32 v[170:171], v[170:171], v[114:115]
	v_cvt_pk_bf16_f32 v20, v164, v165
	v_cvt_pk_bf16_f32 v21, v166, v167
	v_cvt_pk_bf16_f32 v22, v168, v169
	v_cvt_pk_bf16_f32 v23, v170, v171
	global_store_dwordx4 v162, v[20:23], s[10:11]
	v_add_u32_e32 v162, 0x400000, v162
	v_pk_mul_f32 v[164:165], v[124:125], v[150:151] op_sel_hi:[1,0]
	v_pk_mul_f32 v[166:167], v[126:127], v[150:151] op_sel_hi:[1,0]
	v_pk_mul_f32 v[168:169], v[128:129], v[150:151] op_sel_hi:[1,0]
	v_pk_mul_f32 v[170:171], v[130:131], v[150:151] op_sel_hi:[1,0]
	v_pk_mul_f32 v[164:165], v[164:165], v[108:109]
	v_pk_mul_f32 v[166:167], v[166:167], v[110:111]
	v_pk_mul_f32 v[168:169], v[168:169], v[112:113]
	v_pk_mul_f32 v[170:171], v[170:171], v[114:115]
	v_cvt_pk_bf16_f32 v24, v164, v165
	v_cvt_pk_bf16_f32 v25, v166, v167
	v_cvt_pk_bf16_f32 v26, v168, v169
	v_cvt_pk_bf16_f32 v27, v170, v171
	global_store_dwordx4 v162, v[24:27], s[10:11]
	v_add_u32_e32 v162, 0x400000, v162
	v_pk_mul_f32 v[164:165], v[132:133], v[152:153] op_sel_hi:[1,0]
	v_pk_mul_f32 v[166:167], v[134:135], v[152:153] op_sel_hi:[1,0]
	v_pk_mul_f32 v[168:169], v[136:137], v[152:153] op_sel_hi:[1,0]
	v_pk_mul_f32 v[170:171], v[138:139], v[152:153] op_sel_hi:[1,0]
	v_pk_mul_f32 v[164:165], v[164:165], v[108:109]
	v_pk_mul_f32 v[166:167], v[166:167], v[110:111]
	v_pk_mul_f32 v[168:169], v[168:169], v[112:113]
	v_pk_mul_f32 v[170:171], v[170:171], v[114:115]
	v_cvt_pk_bf16_f32 v28, v164, v165
	v_cvt_pk_bf16_f32 v29, v166, v167
	v_cvt_pk_bf16_f32 v30, v168, v169
	v_cvt_pk_bf16_f32 v31, v170, v171
	global_store_dwordx4 v162, v[28:31], s[10:11]
	v_add_u32_e32 v162, 0x400000, v162
	v_pk_mul_f32 v[164:165], v[140:141], v[154:155] op_sel_hi:[1,0]
	v_pk_mul_f32 v[166:167], v[142:143], v[154:155] op_sel_hi:[1,0]
	v_pk_mul_f32 v[168:169], v[144:145], v[154:155] op_sel_hi:[1,0]
	v_pk_mul_f32 v[170:171], v[146:147], v[154:155] op_sel_hi:[1,0]
	v_pk_mul_f32 v[164:165], v[164:165], v[108:109]
	v_pk_mul_f32 v[166:167], v[166:167], v[110:111]
	v_pk_mul_f32 v[168:169], v[168:169], v[112:113]
	v_pk_mul_f32 v[170:171], v[170:171], v[114:115]
	v_cvt_pk_bf16_f32 v32, v164, v165
	v_cvt_pk_bf16_f32 v33, v166, v167
	v_cvt_pk_bf16_f32 v34, v168, v169
	v_cvt_pk_bf16_f32 v35, v170, v171
	global_store_dwordx4 v162, v[32:35], s[10:11]
	v_add_u32_e32 v162, 0x400000, v162
	s_waitcnt vmcnt(8)
	v_lshlrev_b32_e32 v116, 16, v92
	v_and_b32_e32 v117, 0xffff0000, v92
	v_lshlrev_b32_e32 v118, 16, v93
	v_and_b32_e32 v119, 0xffff0000, v93
	v_lshlrev_b32_e32 v120, 16, v94
	v_and_b32_e32 v121, 0xffff0000, v94
	v_lshlrev_b32_e32 v122, 16, v95
	v_and_b32_e32 v123, 0xffff0000, v95
	v_pk_mul_f32 v[148:149], v[116:117], v[116:117]
	v_pk_fma_f32 v[148:149], v[118:119], v[118:119], v[148:149]
	v_pk_fma_f32 v[148:149], v[120:121], v[120:121], v[148:149]
	v_pk_fma_f32 v[148:149], v[122:123], v[122:123], v[148:149]
	s_nop 0
	v_add_f32_e32 v148, v148, v149
	v_lshlrev_b32_e32 v124, 16, v96
	v_and_b32_e32 v125, 0xffff0000, v96
	v_lshlrev_b32_e32 v126, 16, v97
	v_and_b32_e32 v127, 0xffff0000, v97
	v_lshlrev_b32_e32 v128, 16, v98
	v_and_b32_e32 v129, 0xffff0000, v98
	v_lshlrev_b32_e32 v130, 16, v99
	v_and_b32_e32 v131, 0xffff0000, v99
	v_pk_mul_f32 v[150:151], v[124:125], v[124:125]
	v_pk_fma_f32 v[150:151], v[126:127], v[126:127], v[150:151]
	v_pk_fma_f32 v[150:151], v[128:129], v[128:129], v[150:151]
	v_pk_fma_f32 v[150:151], v[130:131], v[130:131], v[150:151]
	s_nop 0
	v_add_f32_e32 v150, v150, v151
	v_lshlrev_b32_e32 v132, 16, v100
	v_and_b32_e32 v133, 0xffff0000, v100
	v_lshlrev_b32_e32 v134, 16, v101
	v_and_b32_e32 v135, 0xffff0000, v101
	v_lshlrev_b32_e32 v136, 16, v102
	v_and_b32_e32 v137, 0xffff0000, v102
	v_lshlrev_b32_e32 v138, 16, v103
	v_and_b32_e32 v139, 0xffff0000, v103
	v_pk_mul_f32 v[152:153], v[132:133], v[132:133]
	v_pk_fma_f32 v[152:153], v[134:135], v[134:135], v[152:153]
	v_pk_fma_f32 v[152:153], v[136:137], v[136:137], v[152:153]
	v_pk_fma_f32 v[152:153], v[138:139], v[138:139], v[152:153]
	s_nop 0
	v_add_f32_e32 v152, v152, v153
	v_lshlrev_b32_e32 v140, 16, v104
	v_and_b32_e32 v141, 0xffff0000, v104
	v_lshlrev_b32_e32 v142, 16, v105
	v_and_b32_e32 v143, 0xffff0000, v105
	v_lshlrev_b32_e32 v144, 16, v106
	v_and_b32_e32 v145, 0xffff0000, v106
	v_lshlrev_b32_e32 v146, 16, v107
	v_and_b32_e32 v147, 0xffff0000, v107
	v_pk_mul_f32 v[154:155], v[140:141], v[140:141]
	v_pk_fma_f32 v[154:155], v[142:143], v[142:143], v[154:155]
	v_pk_fma_f32 v[154:155], v[144:145], v[144:145], v[154:155]
	v_pk_fma_f32 v[154:155], v[146:147], v[146:147], v[154:155]
	s_nop 0
	v_add_f32_e32 v154, v154, v155
	s_nop 1
	v_add_f32_dpp v148, v148, v148 quad_perm:[1,0,3,2] row_mask:0xf bank_mask:0xf
	v_add_f32_dpp v150, v150, v150 quad_perm:[1,0,3,2] row_mask:0xf bank_mask:0xf
	v_add_f32_dpp v152, v152, v152 quad_perm:[1,0,3,2] row_mask:0xf bank_mask:0xf
	v_add_f32_dpp v154, v154, v154 quad_perm:[1,0,3,2] row_mask:0xf bank_mask:0xf
	v_add_f32_dpp v148, v148, v148 quad_perm:[2,3,0,1] row_mask:0xf bank_mask:0xf
	v_add_f32_dpp v150, v150, v150 quad_perm:[2,3,0,1] row_mask:0xf bank_mask:0xf
	v_add_f32_dpp v152, v152, v152 quad_perm:[2,3,0,1] row_mask:0xf bank_mask:0xf
	v_add_f32_dpp v154, v154, v154 quad_perm:[2,3,0,1] row_mask:0xf bank_mask:0xf
	v_add_f32_dpp v148, v148, v148 row_half_mirror row_mask:0xf bank_mask:0xf
	v_add_f32_dpp v150, v150, v150 row_half_mirror row_mask:0xf bank_mask:0xf
	v_add_f32_dpp v152, v152, v152 row_half_mirror row_mask:0xf bank_mask:0xf
	v_add_f32_dpp v154, v154, v154 row_half_mirror row_mask:0xf bank_mask:0xf
	v_add_f32_dpp v148, v148, v148 row_mirror row_mask:0xf bank_mask:0xf
	v_add_f32_dpp v150, v150, v150 row_mirror row_mask:0xf bank_mask:0xf
	v_add_f32_dpp v152, v152, v152 row_mirror row_mask:0xf bank_mask:0xf
	v_add_f32_dpp v154, v154, v154 row_mirror row_mask:0xf bank_mask:0xf
	ds_bpermute_b32 v156, v187, v148
	ds_bpermute_b32 v157, v187, v150
	ds_bpermute_b32 v158, v187, v152
	ds_bpermute_b32 v159, v187, v154
	s_waitcnt lgkmcnt(0)
; __device__ __forceinline__ float bf_lo(unsigned w) { return __uint_as_float(w << 16); }
; __device__ __forceinline__ float bf_hi(unsigned w) { return __uint_as_float(w & 0xffff0000u); }
; __device__ __forceinline__ unsigned cvt_pk_nv(float lo, float hi) { unsigned r; asm("v_cvt_pk_bf16_f32 %0, %1, %2" : "=v"(r) : "v"(lo), "v"(hi)); return r; }
; template <int R>
; __device__ __forceinline__ void rows_norm512(bf16* base, int m0, int stride, int mx, const float* g, int lane) {
;     ...
;     for (int r = 0; r < R; ++r) ss[r] = rsqrtf(wave_sum(ss[r]) * (1.f / 512.f) + EPS);
; #pragma unroll
;     for (int r = 0; r < R; ++r) { const v4u x = w[r]; const float q = ss[r];
;         v4u o; o.x = cvt_pk_nv(bf_lo(x.x) * q * g0.x, bf_hi(x.x) * q * g0.y); o.y = cvt_pk_nv(bf_lo(x.y) * q * g0.z, bf_hi(x.y) * q * g0.w);
;         o.z = cvt_pk_nv(bf_lo(x.z) * q * g1.x, bf_hi(x.z) * q * g1.y); o.w = cvt_pk_nv(bf_lo(x.w) * q * g1.z, bf_hi(x.w) * q * g1.w);
;         if (ok[r]) *(v4u*)(base + (size_t)mr[r] * DM + 8 * lane) = o; }
	v_add_f32_e32 v148, v148, v156
	v_add_f32_e32 v150, v150, v157
	v_add_f32_e32 v152, v152, v158
	v_add_f32_e32 v154, v154, v159
	ds_bpermute_b32 v156, v188, v148
	ds_bpermute_b32 v157, v188, v150
	ds_bpermute_b32 v158, v188, v152
	ds_bpermute_b32 v159, v188, v154
	s_waitcnt lgkmcnt(0)
	v_add_f32_e32 v148, v148, v156
	v_add_f32_e32 v150, v150, v157
	v_add_f32_e32 v152, v152, v158
	v_add_f32_e32 v154, v154, v159
	v_fmamk_f32 v148, v148, 0x3b000000, v160
	v_fmamk_f32 v150, v150, 0x3b000000, v160
	v_fmamk_f32 v152, v152, 0x3b000000, v160
	v_fmamk_f32 v154, v154, 0x3b000000, v160
	v_rsq_f32_e32 v148, v148
	v_rsq_f32_e32 v150, v150
	v_rsq_f32_e32 v152, v152
	v_rsq_f32_e32 v154, v154
	s_nop 1
	v_pk_mul_f32 v[164:165], v[116:117], v[148:149] op_sel_hi:[1,0]
	v_pk_mul_f32 v[166:167], v[118:119], v[148:149] op_sel_hi:[1,0]
	v_pk_mul_f32 v[168:169], v[120:121], v[148:149] op_sel_hi:[1,0]
	v_pk_mul_f32 v[170:171], v[122:123], v[148:149] op_sel_hi:[1,0]
	v_pk_mul_f32 v[164:165], v[164:165], v[108:109]
	v_pk_mul_f32 v[166:167], v[166:167], v[110:111]
	v_pk_mul_f32 v[168:169], v[168:169], v[112:113]
	v_pk_mul_f32 v[170:171], v[170:171], v[114:115]
	v_cvt_pk_bf16_f32 v20, v164, v165
	v_cvt_pk_bf16_f32 v21, v166, v167
	v_cvt_pk_bf16_f32 v22, v168, v169
	v_cvt_pk_bf16_f32 v23, v170, v171
	global_store_dwordx4 v162, v[20:23], s[10:11]
	v_add_u32_e32 v162, 0x400000, v162
	v_pk_mul_f32 v[164:165], v[124:125], v[150:151] op_sel_hi:[1,0]
	v_pk_mul_f32 v[166:167], v[126:127], v[150:151] op_sel_hi:[1,0]
	v_pk_mul_f32 v[168:169], v[128:129], v[150:151] op_sel_hi:[1,0]
	v_pk_mul_f32 v[170:171], v[130:131], v[150:151] op_sel_hi:[1,0]
	v_pk_mul_f32 v[164:165], v[164:165], v[108:109]
	v_pk_mul_f32 v[166:167], v[166:167], v[110:111]
	v_pk_mul_f32 v[168:169], v[168:169], v[112:113]
	v_pk_mul_f32 v[170:171], v[170:171], v[114:115]
	v_cvt_pk_bf16_f32 v24, v164, v165
	v_cvt_pk_bf16_f32 v25, v166, v167
	v_cvt_pk_bf16_f32 v26, v168, v169
	v_cvt_pk_bf16_f32 v27, v170, v171
	global_store_dwordx4 v162, v[24:27], s[10:11]
	v_add_u32_e32 v162, 0x400000, v162
	v_pk_mul_f32 v[164:165], v[132:133], v[152:153] op_sel_hi:[1,0]
	v_pk_mul_f32 v[166:167], v[134:135], v[152:153] op_sel_hi:[1,0]
	v_pk_mul_f32 v[168:169], v[136:137], v[152:153] op_sel_hi:[1,0]
	v_pk_mul_f32 v[170:171], v[138:139], v[152:153] op_sel_hi:[1,0]
	v_pk_mul_f32 v[164:165], v[164:165], v[108:109]
	v_pk_mul_f32 v[166:167], v[166:167], v[110:111]
	v_pk_mul_f32 v[168:169], v[168:169], v[112:113]
	v_pk_mul_f32 v[170:171], v[170:171], v[114:115]
	v_cvt_pk_bf16_f32 v28, v164, v165
	v_cvt_pk_bf16_f32 v29, v166, v167
	v_cvt_pk_bf16_f32 v30, v168, v169
	v_cvt_pk_bf16_f32 v31, v170, v171
	global_store_dwordx4 v162, v[28:31], s[10:11]
	v_add_u32_e32 v162, 0x400000, v162
	v_pk_mul_f32 v[164:165], v[140:141], v[154:155] op_sel_hi:[1,0]
	v_pk_mul_f32 v[166:167], v[142:143], v[154:155] op_sel_hi:[1,0]
	v_pk_mul_f32 v[168:169], v[144:145], v[154:155] op_sel_hi:[1,0]
	v_pk_mul_f32 v[170:171], v[146:147], v[154:155] op_sel_hi:[1,0]
	v_pk_mul_f32 v[164:165], v[164:165], v[108:109]
	v_pk_mul_f32 v[166:167], v[166:167], v[110:111]
	v_pk_mul_f32 v[168:169], v[168:169], v[112:113]
	v_pk_mul_f32 v[170:171], v[170:171], v[114:115]
	v_cvt_pk_bf16_f32 v32, v164, v165
	v_cvt_pk_bf16_f32 v33, v166, v167
	v_cvt_pk_bf16_f32 v34, v168, v169
	v_cvt_pk_bf16_f32 v35, v170, v171
	global_store_dwordx4 v162, v[32:35], s[10:11]
	v_add_u32_e32 v162, 0x400000, v162
	s_branch .LBB0_834
	v_mov_b32_e32 v15, v13
	v_lshl_add_u64 v[16:17], s[16:17], 0, v[12:13]
	v_lshl_add_u64 v[18:19], s[12:13], 0, v[14:15]
	s_mov_b32 s14, 0x3b000000
	v_mov_b32_e32 v20, 0x358637bd
	s_mov_b32 s15, 0x800000
	s_mov_b32 s18, s35
	v_readlane_b32 s36, v232, 5
	s_branch .LBB0_826
